# forgetting attention row-sum: the two 0+x chain heads folded into the first add (bit-identical), on top of the op_sel broadcast folding in the dilated fast path
# baseline (speedup 1.0000x reference)
;     ...
;     float s0 = 0.f, s1 = 0.f;
; #pragma unroll
;     for (int r = 0; r < 16; ++r) {
;         float e0 = __builtin_amdgcn_exp2f(p0[r]), e1 = __builtin_amdgcn_exp2f(p1[r]);
;         if (WMODE == 1) { e0 *= wa[r]; e1 *= wa[r]; }
;         if (WMODE == 4) { const int d0 = dlt0 - ((r & 3) + 8 * (r >> 2)), d1 = d0 - 32;
;             const float w0 = (((unsigned)d0 <= 128u) ? 1.f : 0.f) + ((((unsigned)d0 <= 512u) && ((d0 & 3) == 0)) ? 1.f : 0.f) + ((((unsigned)d0 <= 2048u) && ((d0 & 15) == 0)) ? 1.f : 0.f);
;             const float w1 = (((unsigned)d1 <= 128u) ? 1.f : 0.f) + ((((unsigned)d1 <= 512u) && ((d1 & 3) == 0)) ? 1.f : 0.f) + ((((unsigned)d1 <= 2048u) && ((d1 & 15) == 0)) ? 1.f : 0.f);
;             e0 *= w0; e1 *= w1; }
;         p0[r] = e0; p1[r] = e1; s0 += e0; s1 += e1; }
;     l += s0 + s1;
; template <int MODE> __device__ __forceinline__ void attn_unit(LAS unsigned char* lds, const AttnP& P, int b, int h, int qb) {
;     ...
;                 if (MODE == 0 && 64 * t + 63 > q0w) { int dd = dlt0; asm volatile("" : "+v"(dd)); causal_mask(p0, p1, dd); }
;                 if (MODE == 0) softmax_step<0>(p0, p1, m1, l1, oa0, oa1, first, wm0, 0);
.LBB0_699:
	v_add_f32_e32 v66, v95, v96
	v_add_f32_e32 v67, v108, v109
	v_add_f32_e32 v66, v94, v66
	v_add_f32_e32 v67, v107, v67
	v_add_f32_e32 v66, v93, v66
	v_add_f32_e32 v67, v106, v67
	v_add_f32_e32 v66, v92, v66
	v_add_f32_e32 v67, v81, v67
	v_add_f32_e32 v66, v121, v66
	v_add_f32_e32 v67, v113, v67
	v_add_f32_e32 v66, v120, v66
	v_add_f32_e32 v67, v87, v67
	v_add_f32_e32 v66, v97, v66
	v_add_f32_e32 v67, v86, v67
	v_add_f32_e32 v66, v112, v66
	v_add_f32_e32 v67, v89, v67
	v_add_f32_e32 v66, v111, v66
	v_add_f32_e32 v67, v88, v67
	v_add_f32_e32 v66, v110, v66
	v_add_f32_e32 v67, v83, v67
	v_add_f32_e32 v66, v90, v66
	v_add_f32_e32 v67, v82, v67
	v_add_f32_e32 v66, v78, v66
	v_add_f32_e32 v67, v74, v67
	v_add_f32_e32 v66, v91, v66
	v_add_f32_e32 v67, v84, v67
	v_add_f32_e32 v66, v80, v66
	v_add_f32_e32 v67, v76, v67
	v_add_f32_e32 v66, v79, v66
	v_add_f32_e32 v67, v75, v67
	v_add_f32_e32 v66, v66, v67
	v_add_f32_e32 v209, v209, v66
	s_mov_b64 s[20:21], 0
	s_sub_i32 s4, s16, 63
	s_cmp_gt_i32 s4, s36
	s_cbranch_scc1 .LBB0_666

;     ...
;     float s0 = 0.f, s1 = 0.f;
; #pragma unroll
;     for (int r = 0; r < 16; ++r) {
;         float e0 = __builtin_amdgcn_exp2f(p0[r]), e1 = __builtin_amdgcn_exp2f(p1[r]);
;         if (WMODE == 1) { e0 *= wa[r]; e1 *= wa[r]; }
;         if (WMODE == 4) { const int d0 = dlt0 - ((r & 3) + 8 * (r >> 2)), d1 = d0 - 32;
;             const float w0 = (((unsigned)d0 <= 128u) ? 1.f : 0.f) + ((((unsigned)d0 <= 512u) && ((d0 & 3) == 0)) ? 1.f : 0.f) + ((((unsigned)d0 <= 2048u) && ((d0 & 15) == 0)) ? 1.f : 0.f);
;             const float w1 = (((unsigned)d1 <= 128u) ? 1.f : 0.f) + ((((unsigned)d1 <= 512u) && ((d1 & 3) == 0)) ? 1.f : 0.f) + ((((unsigned)d1 <= 2048u) && ((d1 & 15) == 0)) ? 1.f : 0.f);
;             e0 *= w0; e1 *= w1; }
;         p0[r] = e0; p1[r] = e1; s0 += e0; s1 += e1; }
;     l += s0 + s1;
.LBB0_732:
	v_add_f32_e32 v66, v95, v96
	v_add_f32_e32 v67, v108, v109
	v_add_f32_e32 v66, v94, v66
	v_add_f32_e32 v67, v107, v67
	v_add_f32_e32 v66, v93, v66
	v_add_f32_e32 v67, v106, v67
	v_add_f32_e32 v66, v92, v66
	v_add_f32_e32 v67, v81, v67
	v_add_f32_e32 v66, v121, v66
	v_add_f32_e32 v67, v113, v67
	v_add_f32_e32 v66, v120, v66
	v_add_f32_e32 v67, v87, v67
	v_add_f32_e32 v66, v97, v66
	v_add_f32_e32 v67, v86, v67
	v_add_f32_e32 v66, v112, v66
	v_add_f32_e32 v67, v89, v67
	v_add_f32_e32 v66, v111, v66
	v_add_f32_e32 v67, v88, v67
	v_add_f32_e32 v66, v110, v66
	v_add_f32_e32 v67, v83, v67
	v_add_f32_e32 v66, v90, v66
	v_add_f32_e32 v67, v82, v67
	v_add_f32_e32 v66, v78, v66
	v_add_f32_e32 v67, v74, v67
	v_add_f32_e32 v66, v91, v66
	v_add_f32_e32 v67, v84, v67
	v_add_f32_e32 v66, v80, v66
	v_add_f32_e32 v67, v76, v67
	v_add_f32_e32 v66, v79, v66
	v_add_f32_e32 v67, v75, v67
	v_add_f32_e32 v66, v66, v67
	v_add_f32_e32 v209, v209, v66
	s_mov_b64 s[20:21], 0
	s_andn2_b64 vcc, exec, s[26:27]
	s_cbranch_vccnz .LBB0_661
